# EA on every GEMM unit (not only a call's last one): both wave halves run each epilogue together; skew restored before the next unit's K-loop
# speedup vs baseline: 1.0335x; 1.0161x over previous
; #define LAS __attribute__((address_space(3)))
; #define PG8_WAIT_V(n) asm volatile("s_waitcnt vmcnt(" #n ")" ::: "memory")
; #define PG8_BAR __builtin_amdgcn_s_barrier()
; __device__ __forceinline__ bool gemm_phase(LAS unsigned char* lds, int l, int sub, int gi, bool dry = false) {
;     ...
;         __builtin_amdgcn_sched_barrier(0); asm volatile("" ::: "memory");
;         if (!dry) { GD g2; make_gd((LAS const Params*)(lds + PRM_OFF), l, sub, gi, g2); gemm_epilogue(lds, g2, acc, cur); }
;         if (!has_next) break;
; #pragma unroll
;         for (int a = 0; a < 2; ++a)
; #pragma unroll
;             for (int b = 0; b < 2; ++b)
; #pragma unroll
;                 for (int m = 0; m < 4; ++m)
; #pragma unroll
;                     for (int n = 0; n < 2; ++n) acc[a][b][m][n] = (f32x4){0.f, 0.f, 0.f, 0.f};
;         cur = nxt; cA = nA; cB = nB; ++ui;
;     }
;     PG8_WAIT_V(0);
;     if (wr == 0) PG8_BAR;
;     PG8_BAR;
.LBB0_309:
	v_readfirstlane_b32 s2, v210
	s_nop 3
	s_lshr_b32 s2, s2, 8
	s_cmp_lg_u32 s2, 1
	s_cbranch_scc1 .Lmy_ea_e
	s_barrier

; #define LAS __attribute__((address_space(3)))
; __device__ __forceinline__ bool gemm_phase(LAS unsigned char* lds, int l, int sub, int gi, bool dry = false) {
;     ...
;         __builtin_amdgcn_sched_barrier(0); asm volatile("" ::: "memory");
;         if (!dry) { GD g2; make_gd((LAS const Params*)(lds + PRM_OFF), l, sub, gi, g2); gemm_epilogue(lds, g2, acc, cur); }
.LBB0_385:
	v_readfirstlane_b32 s88, v210
	s_nop 3
	s_lshr_b32 s88, s88, 8
	s_cmp_lg_u32 s88, 0
	s_cbranch_scc1 .Lmy_ea_s
	s_barrier
